# FoX: besides the next key tile's loads, also touch the tile after it (4 discarded 16B loads per lane) so the following iteration's real loads hit L2; staging waits adjusted by +4
# baseline (speedup 1.0000x reference)
; DI void fox_attn(const Params& P, int bh, int qb, unsigned char* smem, int tt) {
;     ...
;         if (more) {
;             const bf16_t* kg2 = kg + (size_t)(kt + 1) * 64 * 1024; const bf16_t* vg2 = vg + (kt + 1) * 64;
;             rk0 = *(const u32x4*)kg2; rk1 = *(const u32x4*)(kg2 + 32 * 1024);
;             rv0 = *(const u32x4*)vg2; rv1 = *(const u32x4*)(vg2 + 32 * TSEQ);
;             if (tid < 64) rc = cf[(kt + 1) * 64 + tid] * L2E;
;         }
.LBB0_549:
	s_or_b64 exec, exec, s[38:39]
	v_lshl_add_u64 v[186:187], v[36:37], 0, s[18:19]
	v_lshl_add_u64 v[188:189], v[108:109], 0, s[18:19]
	global_load_dwordx4 v[190:193], v[186:187], off
	global_load_dwordx4 v[190:193], v[188:189], off
	v_lshl_add_u64 v[186:187], s[34:35], 1, v[106:107]
	s_mov_b64 s[100:101], 0x20000
	global_load_dwordx4 v[190:193], v[186:187], off offset:128
	v_lshl_add_u64 v[186:187], v[186:187], 0, s[100:101]
	global_load_dwordx4 v[190:193], v[186:187], off offset:128

; DI void fox_attn(const Params& P, int bh, int qb, unsigned char* smem, int tt) {
;     ...
;         {
;             const float sh = cq - m;
;             const f32x2v sh2 = {sh, sh};
;             f32x2v rs2 = {0.f, 0.f};
; #pragma unroll
;             for (int mt = 0; mt < 2; ++mt)
; #pragma unroll
;                 for (int p2 = 0; p2 < 8; ++p2) {
;                     const f32x2v sv = {sacc[mt][2 * p2], sacc[mt][2 * p2 + 1]};
;                     const f32x2v t = sv + sh2;
;                     f32x2v pp; pp.x = __builtin_amdgcn_exp2f(t.x); pp.y = __builtin_amdgcn_exp2f(t.y);
;                     sacc[mt][2 * p2] = pp.x; sacc[mt][2 * p2 + 1] = pp.y;
;                     rs2 = rs2 + pp;
;                 }
;             l += rs2.x + rs2.y;
;         }
;         {
;             u32x4 vw[2][2][2];
; #pragma unroll
;             for (int mt = 0; mt < 2; ++mt)
; #pragma unroll
;                 for (int s = 0; s < 2; ++s)
; #pragma unroll
;                     for (int dt = 0; dt < 2; ++dt) {
;                         const bf16_t* vp = VTs + (dt * 32 + r) * 72 + mt * 32 + 16 * s + 4 * h2;
;                         const u32x2 lo = *(const u32x2*)vp, hi = *(const u32x2*)(vp + 8);
;                         vw[mt][s][dt].x = lo.x; vw[mt][s][dt].y = lo.y; vw[mt][s][dt].z = hi.x; vw[mt][s][dt].w = hi.y;
;                     }
;             u32x4 pw[2][2];
; #pragma unroll
;             for (int mt = 0; mt < 2; ++mt)
; #pragma unroll
;                 for (int s = 0; s < 2; ++s) {
;                     pw[mt][s].x = pack2(sacc[mt][8 * s + 0], sacc[mt][8 * s + 1]); pw[mt][s].y = pack2(sacc[mt][8 * s + 2], sacc[mt][8 * s + 3]);
;                     pw[mt][s].z = pack2(sacc[mt][8 * s + 4], sacc[mt][8 * s + 5]); pw[mt][s].w = pack2(sacc[mt][8 * s + 6], sacc[mt][8 * s + 7]);
;                 }
;             __builtin_amdgcn_sched_barrier(0);
; #pragma unroll
;             for (int mt = 0; mt < 2; ++mt)
; #pragma unroll
;                 for (int s = 0; s < 2; ++s) {
;                     const bf16x8 pf = __builtin_bit_cast(bf16x8, pw[mt][s]);
;                     O[0] = MFMA32(__builtin_bit_cast(bf16x8, vw[mt][s][0]), pf, O[0]);
;                     O[1] = MFMA32(__builtin_bit_cast(bf16x8, vw[mt][s][1]), pf, O[1]);
;                 }
;         }
;         if (more) {
;             unsigned char* bufn = smem + ((kt + 1) & 1) * BUFB;
.LBB0_554:
	v_sub_f32_e32 v132, v121, v128
	v_pk_add_f32 v[44:45], v[110:111], v[132:133] op_sel_hi:[1,0]
	v_lshlrev_b32_e32 v110, 1, v124
	v_add3_u32 v0, v0, v126, v110
	v_add_u32_e32 v129, 0x2000, v0
	v_add_u32_e32 v0, 0x3000, v0
	v_pk_add_f32 v[46:47], v[50:51], v[132:133] op_sel_hi:[1,0]
	v_pk_add_f32 v[48:49], v[114:115], v[132:133] op_sel_hi:[1,0]
	v_pk_add_f32 v[50:51], v[54:55], v[132:133] op_sel_hi:[1,0]
	v_pk_add_f32 v[54:55], v[112:113], v[132:133] op_sel_hi:[1,0]
	v_pk_add_f32 v[58:59], v[58:59], v[132:133] op_sel_hi:[1,0]
	v_pk_add_f32 v[64:65], v[116:117], v[132:133] op_sel_hi:[1,0]
	v_pk_add_f32 v[56:57], v[56:57], v[132:133] op_sel_hi:[1,0]
	v_pk_add_f32 v[62:63], v[62:63], v[132:133] op_sel_hi:[1,0]
	v_pk_add_f32 v[52:53], v[52:53], v[132:133] op_sel_hi:[1,0]
	v_pk_add_f32 v[60:61], v[60:61], v[132:133] op_sel_hi:[1,0]
	v_pk_add_f32 v[38:39], v[38:39], v[132:133] op_sel_hi:[1,0]
	v_pk_add_f32 v[42:43], v[42:43], v[132:133] op_sel_hi:[1,0]
	v_pk_add_f32 v[36:37], v[36:37], v[132:133] op_sel_hi:[1,0]
	v_pk_add_f32 v[40:41], v[40:41], v[132:133] op_sel_hi:[1,0]
	v_pk_add_f32 v[34:35], v[34:35], v[132:133] op_sel_hi:[1,0]
	ds_read2_b64 v[110:113], v129 offset0:128 offset1:130
	ds_read2_b64 v[114:117], v129 offset0:132 offset1:134
	ds_read2_b64 v[132:135], v0 offset0:192 offset1:194
	ds_read2_b64 v[136:139], v0 offset0:196 offset1:198
	ds_read2_b64 v[140:143], v129 offset0:136 offset1:138
	ds_read2_b64 v[144:147], v0 offset0:200 offset1:202
	ds_read2_b64 v[148:151], v129 offset0:140 offset1:142
	ds_read2_b64 v[152:155], v0 offset0:204 offset1:206
	v_exp_f32_e32 v44, v44
	v_exp_f32_e32 v45, v45
	v_exp_f32_e32 v46, v46
	v_exp_f32_e32 v47, v47
	v_exp_f32_e32 v48, v48
	v_exp_f32_e32 v49, v49
	v_exp_f32_e32 v50, v50
	v_exp_f32_e32 v51, v51
	v_exp_f32_e32 v54, v54
	v_exp_f32_e32 v55, v55
	v_exp_f32_e32 v58, v58
	v_exp_f32_e32 v59, v59
	v_exp_f32_e32 v64, v64
	v_exp_f32_e32 v65, v65
	v_exp_f32_e32 v56, v56
	v_exp_f32_e32 v57, v57
	v_exp_f32_e32 v62, v62
	v_exp_f32_e32 v63, v63
	v_exp_f32_e32 v52, v52
	v_exp_f32_e32 v53, v53
	v_exp_f32_e32 v60, v60
	v_exp_f32_e32 v61, v61
	v_exp_f32_e32 v38, v38
	v_exp_f32_e32 v39, v39
	v_exp_f32_e32 v42, v42
	v_exp_f32_e32 v43, v43
	v_exp_f32_e32 v36, v36
	v_exp_f32_e32 v37, v37
	v_exp_f32_e32 v40, v40
	v_exp_f32_e32 v41, v41
	v_exp_f32_e32 v34, v34
	v_exp_f32_e32 v35, v35
	v_cvt_pk_bf16_f32 v156, v44, v45
	v_cvt_pk_bf16_f32 v157, v46, v47
	v_cvt_pk_bf16_f32 v158, v48, v49
	v_cvt_pk_bf16_f32 v159, v50, v51
	v_cvt_pk_bf16_f32 v160, v54, v55
	v_cvt_pk_bf16_f32 v161, v58, v59
	v_cvt_pk_bf16_f32 v162, v64, v65
	v_cvt_pk_bf16_f32 v163, v56, v57
	v_cvt_pk_bf16_f32 v170, v62, v63
	v_cvt_pk_bf16_f32 v171, v52, v53
	v_cvt_pk_bf16_f32 v172, v60, v61
	v_cvt_pk_bf16_f32 v173, v38, v39
	v_cvt_pk_bf16_f32 v174, v42, v43
	v_cvt_pk_bf16_f32 v175, v36, v37
	v_cvt_pk_bf16_f32 v176, v40, v41
	v_cvt_pk_bf16_f32 v177, v34, v35
	s_waitcnt lgkmcnt(7)
	v_mfma_f32_32x32x16_bf16 v[18:33], v[110:113], v[156:159], v[18:33]
	s_waitcnt lgkmcnt(5)
	v_mfma_f32_32x32x16_bf16 v[2:17], v[132:135], v[156:159], v[2:17]
	v_mfma_f32_32x32x16_bf16 v[18:33], v[114:117], v[160:163], v[18:33]
	s_waitcnt lgkmcnt(4)
	v_mfma_f32_32x32x16_bf16 v[2:17], v[136:139], v[160:163], v[2:17]
	s_waitcnt lgkmcnt(3)
	v_mfma_f32_32x32x16_bf16 v[18:33], v[140:143], v[170:173], v[18:33]
	s_waitcnt lgkmcnt(2)
	v_mfma_f32_32x32x16_bf16 v[2:17], v[144:147], v[170:173], v[2:17]
	s_waitcnt lgkmcnt(1)
	v_mfma_f32_32x32x16_bf16 v[18:33], v[148:151], v[174:177], v[18:33]
	s_waitcnt lgkmcnt(0)
	v_mfma_f32_32x32x16_bf16 v[2:17], v[152:155], v[174:177], v[2:17]
	s_and_saveexec_b64 s[36:37], s[2:3]
	s_cbranch_execz .LBB0_545
	s_bitcmp1_b32 s47, 0
	s_cselect_b32 s2, 0x4900, 0
	v_add_u32_e32 v0, s2, v131
	v_add3_u32 v110, v0, v119, v104
	s_waitcnt vmcnt(7)
	ds_write_b128 v110, v[82:85]
	s_waitcnt vmcnt(6)
	ds_write_b128 v110, v[86:89] offset:4608
	s_waitcnt vmcnt(5)
	ds_write_b128 v110, v[90:93] offset:9216
	s_waitcnt vmcnt(4)
	ds_write_b128 v110, v[94:97] offset:13824
	s_and_b64 exec, exec, s[0:1]
	s_cbranch_execz .LBB0_545
	v_mul_f32_e32 v118, 0x3fb8aa3b, v118
	v_lshl_add_u32 v0, v130, 2, v0
	ds_write_b32 v0, v118 offset:18432
	s_branch .LBB0_545
